# attention: redundant end-of-unit vmcnt(0) drain removed (next branch start drains before reusing the ring)
# baseline (speedup 1.0000x reference)
; __device__ __forceinline__ int vbid() { return __builtin_amdgcn_readfirstlane((int)((volatile LAS_ unsigned*)((LAS_ unsigned char*)smem + 131072))[3]); }
; DI void attn_phase(const Params& p, const int layer, const int wid_s) {
;     ...
;   for (int it = 0; it * (int)gridDim.x < nunits; ++it) {
;     const int vb = vbid();
;     const int uid = it * (int)gridDim.x + vb;
;     const bool active = uid < nunits;
;     ...
;       asm volatile("s_waitcnt vmcnt(0)" ::: "memory");
;     }
;   }
.LBB0_190:
.LBB0_191:
	s_add_i32 s23, s23, 1
	s_mul_i32 s0, s23, s58
	v_readlane_b32 s48, v249, 37
	v_readlane_b32 s38, v249, 39
	v_readlane_b32 s50, v249, 41
	s_cmpk_gt_i32 s0, 0x7ff
	s_movk_i32 s52, 0xfff
	v_readlane_b32 s53, v250, 39
	s_movk_i32 s26, 0x1fff
	v_readlane_b32 s49, v249, 38
	v_readlane_b32 s39, v249, 40
	v_readlane_b32 s51, v249, 42
	s_cbranch_scc1 .LBB0_374
